# prep x->bf16 loop: the row's four loads issued together with counted vmcnt(3) waits instead of load/wait/load/wait (on top of the nt-policy version)
# speedup vs baseline: 1.0032x; 1.0032x over previous
; __device__ __forceinline__ unsigned cvt_pk_bf16(float lo, float hi) { unsigned r; asm volatile("v_cvt_pk_bf16_f32 %0, %1, %2" : "=v"(r) : "v"(lo), "v"(hi)); return r; }
; PHASE_FN void phase_prep(const Params& p, float* ldsf) {
;     ...
;       for (int r = bx * 8 + wid; r < T; r += G * 8) { const float* xr = p.x + (size_t)r * D; float ss = 0.f;
; #pragma unroll
;           for (int i = 0; i < 4; ++i) { const int c = i * 256 + lane * 4; const f32x4 v = *(const f32x4*)(xr + c); ss += (v[0] * v[0] + v[1] * v[1]) + (v[2] * v[2] + v[3] * v[3]);
;               u32x2 w; w.x = cvt_pk_bf16(v[0], v[1]); w.y = cvt_pk_bf16(v[2], v[3]); *(u32x2*)(xb + (size_t)r * D + c) = w; }
; #pragma unroll
;           for (int o = 32; o >= 1; o >>= 1) ss += __shfl_xor(ss, o);
;           if (lane < 16) ssq[(size_t)r * 16 + lane] = lane == 0 ? ss : 0.f; } }
.LBB0_74:
	s_waitcnt lgkmcnt(0)
	global_load_dwordx4 v[18:21], v[4:5], off offset:-2048 nt
	global_load_dwordx4 v[22:25], v[4:5], off offset:-1024 nt
	global_load_dwordx4 v[26:29], v[4:5], off nt
	global_load_dwordx4 v[30:33], v[4:5], off offset:1024 nt
	s_waitcnt vmcnt(3)
	v_cvt_pk_bf16_f32 v250, v18, v19
	v_cvt_pk_bf16_f32 v251, v20, v21
	global_store_dwordx2 v[6:7], v[250:251], off offset:-1024
	s_waitcnt vmcnt(3)
	v_cvt_pk_bf16_f32 v252, v22, v23
	v_cvt_pk_bf16_f32 v253, v24, v25
	global_store_dwordx2 v[6:7], v[252:253], off offset:-512
	s_waitcnt vmcnt(3)
	v_cvt_pk_bf16_f32 v254, v26, v27
	v_cvt_pk_bf16_f32 v255, v28, v29
	global_store_dwordx2 v[6:7], v[254:255], off
	v_cmp_lt_i32_e64 s[6:7], v11, v10
	v_mul_f32_e32 v19, v19, v19
	v_mul_f32_e32 v21, v21, v21
	v_fmac_f32_e32 v19, v18, v18
	v_fmac_f32_e32 v21, v20, v20
	v_add_f32_e32 v18, v19, v21
	v_mul_f32_e32 v19, v23, v23
	v_mul_f32_e32 v20, v25, v25
	v_fmac_f32_e32 v19, v22, v22
	v_fmac_f32_e32 v20, v24, v24
	v_add_f32_e32 v19, v19, v20
	v_add_f32_e32 v18, v18, v19
	v_mul_f32_e32 v19, v27, v27
	v_mul_f32_e32 v20, v29, v29
	v_fmac_f32_e32 v19, v26, v26
	v_fmac_f32_e32 v20, v28, v28
	v_add_f32_e32 v19, v19, v20
	v_add_f32_e32 v18, v18, v19
	s_waitcnt vmcnt(3)
	v_mul_f32_e32 v19, v31, v31
	v_mul_f32_e32 v20, v33, v33
	v_fmac_f32_e32 v19, v30, v30
	v_fmac_f32_e32 v20, v32, v32
	v_cndmask_b32_e64 v17, v1, v11, s[6:7]
	v_add_f32_e32 v19, v19, v20
	v_lshlrev_b32_e32 v17, 2, v17
	v_add_f32_e32 v18, v18, v19
	ds_bpermute_b32 v17, v17, v18
	v_cmp_lt_i32_e64 s[6:7], v12, v10
	v_cvt_pk_bf16_f32 v20, v30, v31
	v_cvt_pk_bf16_f32 v21, v32, v33
	global_store_dwordx2 v[6:7], v[20:21], off offset:512
	s_waitcnt lgkmcnt(0)
	v_add_f32_e32 v17, v18, v17
	v_cndmask_b32_e64 v19, v1, v12, s[6:7]
	v_lshlrev_b32_e32 v19, 2, v19
	ds_bpermute_b32 v18, v19, v17
	v_cmp_lt_i32_e64 s[6:7], v13, v10
	s_waitcnt lgkmcnt(0)
	v_add_f32_e32 v17, v17, v18
	v_cndmask_b32_e64 v19, v1, v13, s[6:7]
	v_lshlrev_b32_e32 v19, 2, v19
	ds_bpermute_b32 v18, v19, v17
	v_cmp_lt_i32_e64 s[6:7], v14, v10
	s_waitcnt lgkmcnt(0)
	v_add_f32_e32 v17, v17, v18
	v_cndmask_b32_e64 v19, v1, v14, s[6:7]
	v_lshlrev_b32_e32 v19, 2, v19
	ds_bpermute_b32 v18, v19, v17
	v_cmp_lt_i32_e64 s[6:7], v15, v10
	s_waitcnt lgkmcnt(0)
	v_add_f32_e32 v17, v17, v18
	v_cndmask_b32_e64 v19, v1, v15, s[6:7]
	v_lshlrev_b32_e32 v19, 2, v19
	ds_bpermute_b32 v18, v19, v17
	v_cmp_lt_i32_e64 s[6:7], v16, v10
	s_waitcnt lgkmcnt(0)
	v_add_f32_e32 v17, v17, v18
	v_cndmask_b32_e64 v19, v1, v16, s[6:7]
	v_lshlrev_b32_e32 v18, 2, v19
	ds_bpermute_b32 v18, v18, v17
	s_and_saveexec_b64 s[6:7], vcc
	s_cbranch_execz .LBB0_73
	s_waitcnt lgkmcnt(0)
	v_add_f32_e32 v17, v17, v18
	v_cndmask_b32_e64 v17, 0, v17, s[4:5]
	global_store_dword v[2:3], v17, off
	s_branch .LBB0_73
